# conv-resched: weight conversions moved from attention phases into idle half-chip slots of gate_up phases 6,8,13
# speedup vs baseline: 1.0113x; 1.0113x over previous
.LBB0_17:
	s_ashr_i32 s4, s4, 6
	v_writelane_b32 v254, s4, 60
	v_readlane_b32 s4, v253, 0
	v_readlane_b32 s10, v253, 6
	v_readlane_b32 s11, v253, 7
	s_add_u32 s4, s10, 0x100000
	v_writelane_b32 v254, s4, 61
	s_addc_u32 s4, s11, 0
	s_add_u32 s44, s10, 0xb100000
	s_addc_u32 s45, s11, 0
	s_add_u32 s46, s10, 0x10900000
	s_addc_u32 s47, s11, 0
	s_add_u32 s22, s10, 0x12100000
	s_addc_u32 s23, s11, 0
	s_add_u32 s52, s10, 0x12900000
	s_addc_u32 s53, s11, 0
	s_add_u32 s24, s10, 0x14900000
	v_readlane_b32 s5, v253, 1
	s_addc_u32 s25, s11, 0
	v_and_b32_e32 v189, 63, v170
	v_writelane_b32 v254, s4, 62
	s_cmp_eq_u32 s87, 1
	s_mov_b64 s[4:5], -1
	v_readlane_b32 s6, v253, 2
	v_readlane_b32 s7, v253, 3
	v_readlane_b32 s8, v253, 4
	v_readlane_b32 s9, v253, 5
	s_cbranch_scc1 .LBB0_150
	v_readlane_b32 s5, v254, 60
	s_mov_b32 s6, 0
	s_mov_b32 s8, 0
	s_mov_b32 s7, 1
	s_mov_b32 s9, 0
	s_cmp_eq_u32 s87, 2
	s_cbranch_scc0 .Lcv_attn
	s_cmp_eq_u32 s28, 0
	s_cbranch_scc0 .Lcv_s2_gemm
	s_lshl_b32 s4, s15, 3
	s_add_i32 s9, s4, s5
	s_lshl_b32 s7, s89, 3
	s_movk_i32 s6, 0xb00
	s_branch .LBB0_32
.Lcv_s2_gemm:
	s_lshl_b32 s4, s90, 1
	s_cmp_ge_i32 s4, s89
	s_cbranch_scc0 .Lcv_attn
	s_cmp_eq_u32 s28, 1
	s_cbranch_scc0 .Lcv_g6
	s_movk_i32 s8, 0xb00
	s_movk_i32 s6, 0x1680
	s_branch .Lcv_half
.Lcv_g6:
	s_cmp_eq_u32 s28, 6
	s_cbranch_scc0 .Lcv_g8
	s_movk_i32 s8, 0x2680
	s_movk_i32 s6, 0x3400
	s_branch .Lcv_half
.Lcv_g8:
	s_cmp_eq_u32 s28, 8
	s_cbranch_scc0 .Lcv_g13
	s_movk_i32 s8, 0x3400
	s_movk_i32 s6, 0x4180
	s_branch .Lcv_half
.Lcv_g13:
	s_cmp_eq_u32 s28, 13
	s_cbranch_scc0 .Lcv_attn
	s_movk_i32 s8, 0x4e80
	s_movk_i32 s6, 0x5400
.Lcv_half:
	s_ashr_i32 s4, s89, 1
	s_sub_i32 s12, s90, s4
	s_lshl_b32 s12, s12, 3
	s_add_i32 s9, s12, s5
	s_sub_i32 s4, s89, s4
	s_lshl_b32 s7, s4, 3
	s_branch .LBB0_32
.Lcv_attn:
	s_cmp_eq_u32 s28, 4
	s_cbranch_scc0 .Lcv_a11
	s_movk_i32 s12, 0x1680
	s_movk_i32 s13, 0x1e80
	s_movk_i32 s14, 0x2680
	s_branch .Lcv_asel
.Lcv_a11:
	s_cmp_eq_u32 s28, 11
	s_cbranch_scc0 .LBB0_32
	s_movk_i32 s12, 0x4180
	s_movk_i32 s13, 0x4800
	s_movk_i32 s14, 0x4e80
.Lcv_asel:
	s_lshl_b32 s4, s15, 2
	s_and_b32 s4, s4, -8
	s_add_i32 s9, s4, s5
	s_lshl_b32 s4, s89, 2
	s_and_b32 s7, s4, -8
	s_cmp_eq_u32 s87, 0
	s_cbranch_scc0 .Lcv_asub2
	s_bitcmp1_b32 s15, 0
	s_cbranch_scc0 .LBB0_32
	s_mov_b32 s8, s12
	s_mov_b32 s6, s13
	s_branch .LBB0_32
.Lcv_asub2:
	s_bitcmp1_b32 s15, 0
	s_cbranch_scc1 .LBB0_32
	s_mov_b32 s8, s13
	s_mov_b32 s6, s14
